# speedup vs baseline: 1.0052x; 1.0052x over previous
; #define SBAR() __builtin_amdgcn_sched_barrier(0)
; #define SLOAD(i, t) do { const long rb_ = TROW(t); const char* vt_ = (const char*)Vh + rb_ * (LDK * 2); const char* kt_ = (const char*)Kh + rb_ * (LDK * 2); \
;     sr_[i].vs0 = *(const bf16x8*)(vt_ + lo0); sr_[i].vs1 = *(const bf16x8*)(vt_ + lo0 + 32 * LDK * 2); \
;     sr_[i].ks0 = *(const bf16x8*)(kt_ + lo0); sr_[i].ks1 = *(const bf16x8*)(kt_ + lo0 + 32 * LDK * 2); } while (0)
; __device__ __forceinline__ void finishSM(f32x16& p0, f32x16& p1, float alpha, float& l_reg, bf16x8& pa0, bf16x8& pa1, bf16x8& pa2, bf16x8& pa3) {
; #pragma unroll
;   for (int r = 0; r < 16; ++r) p1[r] = __builtin_amdgcn_exp2f(p1[r]);
;   float ps = 0;
; #pragma unroll
;   for (int r = 0; r < 16; ++r) ps += p0[r];
; #pragma unroll
;   for (int r = 0; r < 16; ++r) ps += p1[r];
;   { auto rr = __builtin_amdgcn_permlane32_swap(__float_as_uint(ps), __float_as_uint(ps), false, false);
;     ps = __uint_as_float(rr[0]) + __uint_as_float(rr[1]); }
;   l_reg = l_reg * alpha + ps;
;     ...
;   PK4(p0, 0, pa0); PK4(p0, 8, pa1); PK4(p1, 0, pa2); PK4(p1, 8, pa3);
;     ...
; }
; __device__ __forceinline__ void qkt(f32x16& p0, f32x16& p1, const bf16_t* Ks, const bf16x8* qr, int r32, int hi) {
;   p0 = f32x16{}; p1 = f32x16{};
; #pragma unroll
;   for (int d0 = 0; d0 < 8; ++d0) { int cb = (d0 * 16 + hi * 8) * 2;
;     bf16x8 b0 = *reinterpret_cast<const bf16x8*>((const char*)Ks + KSWZ(r32, cb));
;     bf16x8 b1 = *reinterpret_cast<const bf16x8*>((const char*)Ks + KSWZ(32 + r32, cb));
;     p0 = __builtin_amdgcn_mfma_f32_32x32x16_bf16(b0, qr[d0], p0, 0, 0, 0);
;     p1 = __builtin_amdgcn_mfma_f32_32x32x16_bf16(b1, qr[d0], p1, 0, 0, 0); }
; }
; template <bool META>
; __device__ __forceinline__ void attn_unit(const bf16_t* Q, bf16_t* Oo, const bf16_t* __restrict__ Kb, const bf16_t* __restrict__ Vb, int b, int kvh, int h, int qb, char* lds, const int tid, const float* qn, const float* RT) {
;     ...
;   for (int j = 1; j + 1 < NT; j += 2) {
;     const int bn = bc == 2 ? 0 : bc + 1, bp = bc == 0 ? 2 : bc - 1;
;     SBAR(); qkt(pB0, pB1, (bf16_t*)((char*)K_lds + bc * SHM_K), qr, r32, hi);
;     finishSM(pA0, pA1, alA, l_reg, pa0, pa1, pa2, pa3); SBAR();
;     SLOAD(SO, j + 1);
.LBB0_260:
	s_mov_b32 s6, s28
	v_sub_co_u32_e64 v66, s[0:1], s6, 1
	s_and_b64 s[0:1], s[0:1], exec
	v_readfirstlane_b32 s0, v66
	s_cselect_b32 s28, 2, s0
	s_lshl_b32 s9, s6, 14
	s_add_i32 s0, s9, 0
	v_add_u32_e32 v195, s0, v182
	ds_read_b128 v[66:69], v195 offset:49152
	ds_read_b128 v[70:73], v195 offset:50176
	ds_read_b128 v[210:213], v195 offset:51200
	ds_read_b128 v[214:217], v195 offset:52224
	s_waitcnt lgkmcnt(3)
	s_setprio 1
	v_mfma_f32_32x32x16_bf16 v[82:97], v[66:69], v[98:101], 0
	v_exp_f32_e32 v144, v144
	v_exp_f32_e32 v145, v145
	v_exp_f32_e32 v142, v142
	v_exp_f32_e32 v143, v143
	v_exp_f32_e32 v140, v140
	v_exp_f32_e32 v141, v141
	v_exp_f32_e32 v138, v138
	s_waitcnt lgkmcnt(2)
	v_mfma_f32_32x32x16_bf16 v[66:81], v[70:73], v[98:101], 0
	v_exp_f32_e32 v139, v139
	v_exp_f32_e32 v136, v136
	v_exp_f32_e32 v137, v137
	v_exp_f32_e32 v134, v134
	v_exp_f32_e32 v135, v135
	v_exp_f32_e32 v132, v132
	v_exp_f32_e32 v133, v133
	s_waitcnt lgkmcnt(1)
	v_mfma_f32_32x32x16_bf16 v[82:97], v[210:213], v[102:105], v[82:97]
	v_exp_f32_e32 v130, v130
	v_exp_f32_e32 v131, v131
	s_waitcnt lgkmcnt(0)
	v_mfma_f32_32x32x16_bf16 v[66:81], v[214:217], v[102:105], v[66:81]
	ds_read_b128 v[210:213], v195 offset:53248
	ds_read_b128 v[214:217], v195 offset:54272
	s_waitcnt lgkmcnt(1)
	v_mfma_f32_32x32x16_bf16 v[82:97], v[210:213], v[106:109], v[82:97]
	s_waitcnt lgkmcnt(0)
	v_mfma_f32_32x32x16_bf16 v[66:81], v[214:217], v[106:109], v[66:81]
	ds_read_b128 v[210:213], v195 offset:55296
	ds_read_b128 v[214:217], v195 offset:56320
	s_waitcnt lgkmcnt(1)
	v_mfma_f32_32x32x16_bf16 v[82:97], v[210:213], v[110:113], v[82:97]
	s_waitcnt lgkmcnt(0)
	v_mfma_f32_32x32x16_bf16 v[66:81], v[214:217], v[110:113], v[66:81]
	ds_read_b128 v[210:213], v195 offset:57344
	ds_read_b128 v[214:217], v195 offset:58368
	s_waitcnt lgkmcnt(1)
	v_mfma_f32_32x32x16_bf16 v[82:97], v[210:213], v[114:117], v[82:97]
	s_waitcnt lgkmcnt(0)
	v_mfma_f32_32x32x16_bf16 v[66:81], v[214:217], v[114:117], v[66:81]
	ds_read_b128 v[210:213], v195 offset:59392
	ds_read_b128 v[214:217], v195 offset:60416
	s_waitcnt lgkmcnt(1)
	v_mfma_f32_32x32x16_bf16 v[82:97], v[210:213], v[118:121], v[82:97]
	s_waitcnt lgkmcnt(0)
	v_mfma_f32_32x32x16_bf16 v[66:81], v[214:217], v[118:121], v[66:81]
	ds_read_b128 v[210:213], v195 offset:61440
	ds_read_b128 v[214:217], v195 offset:62464
	s_waitcnt lgkmcnt(1)
	v_mfma_f32_32x32x16_bf16 v[82:97], v[210:213], v[122:125], v[82:97]
	s_waitcnt lgkmcnt(0)
	v_mfma_f32_32x32x16_bf16 v[66:81], v[214:217], v[122:125], v[66:81]
	ds_read_b128 v[210:213], v195 offset:63488
	ds_read_b128 v[214:217], v195 offset:64512
	v_add_f32_e32 v193, v147, v146
	v_add_f32_e32 v193, v148, v193
	v_add_f32_e32 v193, v159, v193
	v_add_f32_e32 v193, v160, v193
	v_add_f32_e32 v193, v209, v193
	v_add_f32_e32 v193, v149, v193
	v_add_f32_e32 v193, v161, v193
	v_add_f32_e32 v193, v151, v193
	v_add_f32_e32 v193, v153, v193
	v_add_f32_e32 v193, v154, v193
	v_add_f32_e32 v193, v157, v193
	v_add_f32_e32 v193, v152, v193
	v_add_f32_e32 v193, v155, v193
	v_add_f32_e32 v193, v156, v193
	v_add_f32_e32 v193, v158, v193
	v_add_f32_e32 v193, v144, v193
	v_add_f32_e32 v193, v145, v193
	v_add_f32_e32 v193, v142, v193
	v_add_f32_e32 v193, v143, v193
	v_add_f32_e32 v193, v140, v193
	v_add_f32_e32 v193, v141, v193
	v_add_f32_e32 v193, v138, v193
	v_add_f32_e32 v193, v139, v193
	v_add_f32_e32 v193, v136, v193
	v_add_f32_e32 v193, v137, v193
	s_waitcnt lgkmcnt(1)
	v_mfma_f32_32x32x16_bf16 v[82:97], v[210:213], v[126:129], v[82:97]
	v_add_f32_e32 v193, v134, v193
	v_add_f32_e32 v193, v135, v193
	v_add_f32_e32 v193, v132, v193
	v_add_f32_e32 v193, v133, v193
	v_add_f32_e32 v193, v130, v193
	v_add_f32_e32 v193, v131, v193
	v_mov_b32_e32 v195, v193
	s_waitcnt lgkmcnt(0)
	v_mfma_f32_32x32x16_bf16 v[66:81], v[214:217], v[126:129], v[66:81]
	s_setprio 0
	v_cvt_pk_bf16_f32 v146, v146, v147
	v_cvt_pk_bf16_f32 v147, v148, v159
	v_cvt_pk_bf16_f32 v148, v160, v209
	v_permlane32_swap_b32_e32 v193, v195
	v_cvt_pk_bf16_f32 v149, v149, v161
	v_permlane32_swap_b32_e32 v146, v148
	v_cvt_pk_bf16_f32 v210, v151, v153
	v_cvt_pk_bf16_f32 v211, v154, v157
	v_cvt_pk_bf16_f32 v212, v152, v155
	v_cvt_pk_bf16_f32 v213, v156, v158
	v_cvt_pk_bf16_f32 v152, v144, v145
	v_cvt_pk_bf16_f32 v153, v142, v143
	v_cvt_pk_bf16_f32 v154, v140, v141
	v_cvt_pk_bf16_f32 v155, v138, v139
	v_cvt_pk_bf16_f32 v156, v136, v137
	v_cvt_pk_bf16_f32 v157, v134, v135
	v_cvt_pk_bf16_f32 v158, v132, v133
	v_cvt_pk_bf16_f32 v159, v130, v131
	v_permlane32_swap_b32_e32 v147, v149
	v_permlane32_swap_b32_e32 v210, v212
	v_permlane32_swap_b32_e32 v211, v213
	v_permlane32_swap_b32_e32 v152, v154
	v_permlane32_swap_b32_e32 v153, v155
	v_permlane32_swap_b32_e32 v156, v158
	v_permlane32_swap_b32_e32 v157, v159
	s_lshl_b32 s8, s28, 14
	v_add_u32_e32 v151, s8, v178
	ds_read_b64_tr_b16 v[214:215], v151 offset:0
	ds_read_b64_tr_b16 v[216:217], v151 offset:0x800
	ds_read_b64_tr_b16 v[218:219], v151 offset:0x1000
	ds_read_b64_tr_b16 v[220:221], v151 offset:0x1800
	ds_read_b64_tr_b16 v[222:223], v151 offset:0x2000
	ds_read_b64_tr_b16 v[224:225], v151 offset:0x2800
	ds_read_b64_tr_b16 v[226:227], v151 offset:0x3000
	ds_read_b64_tr_b16 v[228:229], v151 offset:0x3800
	s_cmpk_lg_i32 s4, 0xfd
	s_cselect_b64 s[0:1], -1, 0
	s_cmpk_eq_i32 s4, 0xfd
	s_cselect_b64 s[40:41], -1, 0
	s_and_b64 s[10:11], s[40:41], exec
	s_cselect_b32 s11, s44, s91
	s_cselect_b32 s10, s31, s90
	s_lshl_b64 s[10:11], s[10:11], 9
	s_add_i32 s19, s9, 0x4000
	s_cmp_lg_u32 s6, 2
	s_cselect_b32 s19, s19, 0
	s_add_i32 s19, s19, s18
	s_add_u32 s16, s12, s10
	s_addc_u32 s17, s13, s11
	s_mov_b32 m0, s19
	s_nop 0
	global_load_lds_dwordx4 v187, s[16:17]
	s_add_i32 m0, s19, 0x380
	s_nop 0
	global_load_lds_dwordx4 v187, s[16:17] offset:128
	s_add_u32 s16, s14, s10
	s_addc_u32 s17, s15, s11
	s_add_i32 m0, s19, 0xc000
	s_nop 0
	global_load_lds_dwordx4 v188, s[16:17]
	s_add_u32 s16, s16, 0x4000
	s_addc_u32 s17, s17, 0
	s_add_i32 m0, s19, 0xc400
	s_nop 0
	global_load_lds_dwordx4 v188, s[16:17]
	s_waitcnt lgkmcnt(6)
; #define SBAR() __builtin_amdgcn_sched_barrier(0)
; template <int D0> __device__ __forceinline__ void pv_one(f32x16& od, int vb, bf16x8 pa0, bf16x8 pa1, bf16x8 pa2, bf16x8 pa3) {
;   const s16x4 l0 = tr_read<v_rd_off(D0, 0, 0)>(vb), h0 = tr_read<v_rd_off(D0, 0, 1)>(vb), l1 = tr_read<v_rd_off(D0, 1, 0)>(vb), h1 = tr_read<v_rd_off(D0, 1, 1)>(vb);
;   const s16x4 l2 = tr_read<v_rd_off(D0, 2, 0)>(vb), h2 = tr_read<v_rd_off(D0, 2, 1)>(vb), l3 = tr_read<v_rd_off(D0, 3, 0)>(vb), h3 = tr_read<v_rd_off(D0, 3, 1)>(vb);
;   asm volatile("s_waitcnt lgkmcnt(0)" ::: "memory"); SBAR();
;     ...
;   od = __builtin_amdgcn_mfma_f32_32x32x16_bf16(pa0, PK(l0, h0), od, 0, 0, 0);
;   od = __builtin_amdgcn_mfma_f32_32x32x16_bf16(pa1, PK(l1, h1), od, 0, 0, 0);
;   od = __builtin_amdgcn_mfma_f32_32x32x16_bf16(pa2, PK(l2, h2), od, 0, 0, 0);
;   od = __builtin_amdgcn_mfma_f32_32x32x16_bf16(pa3, PK(l3, h3), od, 0, 0, 0);
;     ...
; }
; __device__ __forceinline__ void pv_d0(f32x16* o, int vb, bf16x8 pa0, bf16x8 pa1, bf16x8 pa2, bf16x8 pa3) {
;   pv_one<0>(o[0], vb, pa0, pa1, pa2, pa3); pv_one<1>(o[1], vb, pa0, pa1, pa2, pa3); pv_one<2>(o[2], vb, pa0, pa1, pa2, pa3); pv_one<3>(o[3], vb, pa0, pa1, pa2, pa3);
; }
	s_nop 0
	s_setprio 1
	v_mfma_f32_32x32x16_bf16 v[2:17], v[146:149], v[214:217], v[2:17]
	ds_read_b64_tr_b16 v[214:215], v151 offset:0x200
	ds_read_b64_tr_b16 v[216:217], v151 offset:0xa00
	s_waitcnt lgkmcnt(6)
	v_mfma_f32_32x32x16_bf16 v[2:17], v[210:213], v[218:221], v[2:17]
	ds_read_b64_tr_b16 v[218:219], v151 offset:0x1200
	ds_read_b64_tr_b16 v[220:221], v151 offset:0x1a00
	s_waitcnt lgkmcnt(6)
	v_mfma_f32_32x32x16_bf16 v[2:17], v[152:155], v[222:225], v[2:17]
	ds_read_b64_tr_b16 v[222:223], v151 offset:0x2200
	ds_read_b64_tr_b16 v[224:225], v151 offset:0x2a00
	s_waitcnt lgkmcnt(6)
	v_mfma_f32_32x32x16_bf16 v[2:17], v[156:159], v[226:229], v[2:17]
	ds_read_b64_tr_b16 v[226:227], v151 offset:0x3200
	ds_read_b64_tr_b16 v[228:229], v151 offset:0x3a00
	s_waitcnt lgkmcnt(6)
	v_mfma_f32_32x32x16_bf16 v[50:65], v[146:149], v[214:217], v[50:65]
	ds_read_b64_tr_b16 v[214:215], v151 offset:0x400
	ds_read_b64_tr_b16 v[216:217], v151 offset:0xc00
	s_waitcnt lgkmcnt(6)
	v_mfma_f32_32x32x16_bf16 v[50:65], v[210:213], v[218:221], v[50:65]
	ds_read_b64_tr_b16 v[218:219], v151 offset:0x1400
	ds_read_b64_tr_b16 v[220:221], v151 offset:0x1c00
	s_waitcnt lgkmcnt(6)
	v_mfma_f32_32x32x16_bf16 v[50:65], v[152:155], v[222:225], v[50:65]
	ds_read_b64_tr_b16 v[222:223], v151 offset:0x2400
	ds_read_b64_tr_b16 v[224:225], v151 offset:0x2c00
	s_waitcnt lgkmcnt(6)
	v_mfma_f32_32x32x16_bf16 v[50:65], v[156:159], v[226:229], v[50:65]
	ds_read_b64_tr_b16 v[226:227], v151 offset:0x3400
	ds_read_b64_tr_b16 v[228:229], v151 offset:0x3c00
	s_waitcnt lgkmcnt(6)
	v_mfma_f32_32x32x16_bf16 v[34:49], v[146:149], v[214:217], v[34:49]
	ds_read_b64_tr_b16 v[214:215], v151 offset:0x600
	ds_read_b64_tr_b16 v[216:217], v151 offset:0xe00
	s_waitcnt lgkmcnt(6)
	v_mfma_f32_32x32x16_bf16 v[34:49], v[210:213], v[218:221], v[34:49]
	ds_read_b64_tr_b16 v[218:219], v151 offset:0x1600
	ds_read_b64_tr_b16 v[220:221], v151 offset:0x1e00
	s_waitcnt lgkmcnt(6)
	v_mfma_f32_32x32x16_bf16 v[34:49], v[152:155], v[222:225], v[34:49]
	ds_read_b64_tr_b16 v[222:223], v151 offset:0x2600
	ds_read_b64_tr_b16 v[224:225], v151 offset:0x2e00
	s_waitcnt lgkmcnt(6)
	v_mfma_f32_32x32x16_bf16 v[34:49], v[156:159], v[226:229], v[34:49]
	ds_read_b64_tr_b16 v[226:227], v151 offset:0x3600
	ds_read_b64_tr_b16 v[228:229], v151 offset:0x3e00
	s_waitcnt lgkmcnt(6)
	v_mfma_f32_32x32x16_bf16 v[18:33], v[146:149], v[214:217], v[18:33]
	v_max_f32_e32 v146, v82, v83
	v_max3_f32 v146, v146, v84, v85
	v_max3_f32 v146, v146, v86, v87
	v_max3_f32 v146, v146, v88, v89
	v_max3_f32 v146, v146, v90, v91
	v_max3_f32 v146, v146, v92, v93
	v_max3_f32 v146, v146, v94, v95
	v_max3_f32 v146, v146, v96, v97
	v_max3_f32 v146, v146, v66, v67
	s_waitcnt lgkmcnt(4)
	v_mfma_f32_32x32x16_bf16 v[18:33], v[210:213], v[218:221], v[18:33]
	v_max3_f32 v146, v146, v68, v69
	v_max3_f32 v146, v146, v70, v71
	v_max3_f32 v146, v146, v72, v73
	v_max3_f32 v146, v146, v74, v75
	v_max3_f32 v146, v146, v76, v77
	v_max3_f32 v146, v146, v78, v79
	v_max3_f32 v146, v146, v80, v81
	v_mov_b32_e32 v147, v146
	s_waitcnt lgkmcnt(2)
	v_mfma_f32_32x32x16_bf16 v[18:33], v[152:155], v[222:225], v[18:33]
	s_nop 0
	v_permlane32_swap_b32_e32 v146, v147
	v_max_f32_e32 v146, v146, v147
	v_sub_f32_e32 v147, v146, v150
	v_cmp_ge_f32_e32 vcc, s25, v147
	v_max_f32_e32 v146, v150, v146
	v_sub_f32_e32 v147, v150, v146
	s_cmp_eq_u64 vcc, exec
	v_mul_f32_e32 v147, 0x3e0293ee, v147
	s_waitcnt lgkmcnt(0)
	v_mfma_f32_32x32x16_bf16 v[18:33], v[156:159], v[226:229], v[18:33]
	s_setprio 0
	s_cselect_b64 s[42:43], -1, 0
	v_exp_f32_e32 v147, v147
	s_add_i32 s7, s9, 0x4000
	s_cmp_lg_u32 s6, 2
	s_cselect_b32 s6, s7, 0
	s_add_i32 s10, s6, 0
	v_cndmask_b32_e64 v196, v147, 1.0, s[42:43]
	v_cmp_gt_f32_e32 vcc, 1.0, v196
	s_cbranch_vccz .LBB0_264
	s_and_saveexec_b64 s[6:7], s[38:39]
	ds_write_b32 v190, v196 offset:128
	s_or_b64 exec, exec, s[6:7]
	s_waitcnt lgkmcnt(0)
	v_add_u32_e32 v147, v173, v181
	ds_read_b128 v[152:155], v147 offset:224
	ds_read_b128 v[156:159], v147 offset:192
	ds_read_b128 v[210:213], v147 offset:160
	ds_read_b128 v[214:217], v147 offset:128
	s_waitcnt lgkmcnt(3)
	v_pk_mul_f32 v[14:15], v[14:15], v[152:153]
	s_waitcnt lgkmcnt(2)
	v_pk_mul_f32 v[10:11], v[10:11], v[156:157]
	s_waitcnt lgkmcnt(1)
	v_pk_mul_f32 v[6:7], v[6:7], v[210:211]
	v_pk_mul_f32 v[16:17], v[16:17], v[154:155]
	v_pk_mul_f32 v[12:13], v[12:13], v[158:159]
	v_pk_mul_f32 v[8:9], v[8:9], v[212:213]
	s_waitcnt lgkmcnt(0)
	v_pk_mul_f32 v[4:5], v[4:5], v[216:217]
	v_pk_mul_f32 v[2:3], v[2:3], v[214:215]
	v_pk_mul_f32 v[62:63], v[62:63], v[152:153]
	v_pk_mul_f32 v[58:59], v[58:59], v[156:157]
	v_pk_mul_f32 v[54:55], v[54:55], v[210:211]
	v_pk_mul_f32 v[64:65], v[64:65], v[154:155]
	v_pk_mul_f32 v[60:61], v[60:61], v[158:159]
	v_pk_mul_f32 v[56:57], v[56:57], v[212:213]
	v_pk_mul_f32 v[52:53], v[52:53], v[216:217]
	v_pk_mul_f32 v[50:51], v[50:51], v[214:215]
	v_pk_mul_f32 v[46:47], v[46:47], v[152:153]
	v_pk_mul_f32 v[42:43], v[42:43], v[156:157]
	v_pk_mul_f32 v[38:39], v[38:39], v[210:211]
	v_pk_mul_f32 v[48:49], v[48:49], v[154:155]
	v_pk_mul_f32 v[44:45], v[44:45], v[158:159]
	v_pk_mul_f32 v[40:41], v[40:41], v[212:213]
	v_pk_mul_f32 v[36:37], v[36:37], v[216:217]
	v_pk_mul_f32 v[34:35], v[34:35], v[214:215]
	v_pk_mul_f32 v[30:31], v[30:31], v[152:153]
	v_pk_mul_f32 v[26:27], v[26:27], v[156:157]
	v_pk_mul_f32 v[22:23], v[22:23], v[210:211]
	v_pk_mul_f32 v[32:33], v[32:33], v[154:155]
	v_pk_mul_f32 v[28:29], v[28:29], v[158:159]
	v_pk_mul_f32 v[24:25], v[24:25], v[212:213]
	v_pk_mul_f32 v[20:21], v[20:21], v[216:217]
	v_pk_mul_f32 v[18:19], v[18:19], v[214:215]
; #define SBAR() __builtin_amdgcn_sched_barrier(0)
; #define SWRITE(bb, i) do { *(bf16x8*)((char*)V_lds + (bb) * SHM_V + vst0) = sr_[i].vs0;          \
;     *(bf16x8*)((char*)V_lds + (bb) * SHM_V + vst1) = sr_[i].vs1; int kc = sc * 2;               \
;     *(bf16x8*)((char*)K_lds + (bb) * SHM_K + KSWZ(sr, kc)) = sr_[i].ks0;                       \
;     *(bf16x8*)((char*)K_lds + (bb) * SHM_K + KSWZ(32 + sr, kc)) = sr_[i].ks1; } while (0)
; #define SWAIT() asm volatile("s_waitcnt vmcnt(0)" ::: "memory")
; #define RESC(a) do { if (__any((a) < 1.f)) { if (hi == 0) al_l[r32] = (a); asm volatile("s_waitcnt lgkmcnt(0)" ::: "memory"); \
;     _Pragma("unroll") for (int d = 0; d < 4; ++d) _Pragma("unroll") for (int r = 0; r < 16; ++r) o[d][r] *= al_l[crow(r, hi)]; } } while (0)
; __device__ __forceinline__ void partialSM(f32x16& p0, f32x16& p1, float& m_reg, float& mn, float& alpha) {
;     ...
;   if (__builtin_expect(__all(pmax - m_reg <= ATHR / ASCALE), 1)) { mn = m_reg; alpha = 1.f; }
;   else { mn = fmaxf(m_reg, pmax); alpha = __builtin_amdgcn_exp2f((m_reg - mn) * C); m_reg = mn; }
;   float mnC = -mn * C;
; #pragma unroll
;   for (int r = 0; r < 16; ++r) p0[r] = fmaf(p0[r], C, mnC);
; #pragma unroll
;   for (int r = 0; r < 16; ++r) p1[r] = fmaf(p1[r], C, mnC);
; #pragma unroll
;   for (int r = 0; r < 16; ++r) p0[r] = __builtin_amdgcn_exp2f(p0[r]);
; template <bool META>
; __device__ __forceinline__ void attn_unit(const bf16_t* Q, bf16_t* Oo, const bf16_t* __restrict__ Kb, const bf16_t* __restrict__ Vb, int b, int kvh, int h, int qb, char* lds, const int tid, const float* qn, const float* RT) {
;     ...
;     pv_d0(o, vb0 + bp * (int)SHM_V, pa0, pa1, pa2, pa3); partialSM(pB0, pB1, m_reg, mnB, alB);
;     SWAIT(); SWRITE(bn, SE);
;     RESC(alB); __syncthreads();
;     SBAR(); qkt(pA0, pA1, (bf16_t*)((char*)K_lds + bn * SHM_K), qr, r32, hi);
.LBB0_264:
	v_cndmask_b32_e64 v209, v146, v150, s[42:43]
	v_mul_f32_e32 v154, 0xbe0293ee, v209
	s_add_i32 s4, s4, 2
	v_fmamk_f32 v82, v82, 0x3e0293ee, v154
	v_fmamk_f32 v83, v83, 0x3e0293ee, v154
	v_fmamk_f32 v84, v84, 0x3e0293ee, v154
	v_fmamk_f32 v85, v85, 0x3e0293ee, v154
	v_fmamk_f32 v86, v86, 0x3e0293ee, v154
	v_fmamk_f32 v87, v87, 0x3e0293ee, v154
	v_fmamk_f32 v88, v88, 0x3e0293ee, v154
	v_fmamk_f32 v89, v89, 0x3e0293ee, v154
	v_fmamk_f32 v90, v90, 0x3e0293ee, v154
	v_fmamk_f32 v91, v91, 0x3e0293ee, v154
	v_fmamk_f32 v92, v92, 0x3e0293ee, v154
	v_fmamk_f32 v93, v93, 0x3e0293ee, v154
	v_fmamk_f32 v94, v94, 0x3e0293ee, v154
	v_fmamk_f32 v95, v95, 0x3e0293ee, v154
	v_fmamk_f32 v96, v96, 0x3e0293ee, v154
	v_fmamk_f32 v97, v97, 0x3e0293ee, v154
	v_fmamk_f32 v155, v66, 0x3e0293ee, v154
	v_fmamk_f32 v156, v67, 0x3e0293ee, v154
	v_fmamk_f32 v157, v68, 0x3e0293ee, v154
	v_fmamk_f32 v158, v69, 0x3e0293ee, v154
	v_fmamk_f32 v159, v70, 0x3e0293ee, v154
	v_fmamk_f32 v160, v71, 0x3e0293ee, v154
	v_fmamk_f32 v161, v72, 0x3e0293ee, v154
	v_fmamk_f32 v198, v73, 0x3e0293ee, v154
	v_fmamk_f32 v199, v74, 0x3e0293ee, v154
	v_fmamk_f32 v200, v75, 0x3e0293ee, v154
	v_fmamk_f32 v201, v76, 0x3e0293ee, v154
	v_fmamk_f32 v202, v77, 0x3e0293ee, v154
	v_fmamk_f32 v203, v78, 0x3e0293ee, v154
	v_fmamk_f32 v204, v79, 0x3e0293ee, v154
	v_fmamk_f32 v205, v80, 0x3e0293ee, v154
	v_fmac_f32_e32 v154, 0x3e0293ee, v81
	v_exp_f32_e32 v206, v82
	v_exp_f32_e32 v207, v83
	v_exp_f32_e32 v212, v84
	v_exp_f32_e32 v213, v85
	v_exp_f32_e32 v214, v86
	v_exp_f32_e32 v215, v87
	v_exp_f32_e32 v216, v88
	v_exp_f32_e32 v217, v89
	v_exp_f32_e32 v218, v90
	v_exp_f32_e32 v219, v91
	v_exp_f32_e32 v220, v92
	v_exp_f32_e32 v221, v93
	v_exp_f32_e32 v222, v94
	v_exp_f32_e32 v223, v95
	v_exp_f32_e32 v224, v96
	v_exp_f32_e32 v225, v97
	s_waitcnt vmcnt(0)
	s_waitcnt lgkmcnt(0)
	s_barrier
; __device__ __forceinline__ void finishSM(f32x16& p0, f32x16& p1, float alpha, float& l_reg, bf16x8& pa0, bf16x8& pa1, bf16x8& pa2, bf16x8& pa3) {
; #pragma unroll
;   for (int r = 0; r < 16; ++r) p1[r] = __builtin_amdgcn_exp2f(p1[r]);
;   float ps = 0;
; #pragma unroll
;   for (int r = 0; r < 16; ++r) ps += p0[r];
; #pragma unroll
;   for (int r = 0; r < 16; ++r) ps += p1[r];
;   { auto rr = __builtin_amdgcn_permlane32_swap(__float_as_uint(ps), __float_as_uint(ps), false, false);
;     ps = __uint_as_float(rr[0]) + __uint_as_float(rr[1]); }
;   l_reg = l_reg * alpha + ps;
;     ...
;   PK4(p0, 0, pa0); PK4(p0, 8, pa1); PK4(p1, 0, pa2); PK4(p1, 8, pa3);
;     ...
; }
; __device__ __forceinline__ void qkt(f32x16& p0, f32x16& p1, const bf16_t* Ks, const bf16x8* qr, int r32, int hi) {
;   p0 = f32x16{}; p1 = f32x16{};
; #pragma unroll
;   for (int d0 = 0; d0 < 8; ++d0) { int cb = (d0 * 16 + hi * 8) * 2;
;     bf16x8 b0 = *reinterpret_cast<const bf16x8*>((const char*)Ks + KSWZ(r32, cb));
;     bf16x8 b1 = *reinterpret_cast<const bf16x8*>((const char*)Ks + KSWZ(32 + r32, cb));
;     p0 = __builtin_amdgcn_mfma_f32_32x32x16_bf16(b0, qr[d0], p0, 0, 0, 0);
;     p1 = __builtin_amdgcn_mfma_f32_32x32x16_bf16(b1, qr[d0], p1, 0, 0, 0); }
; }
; __device__ __forceinline__ int v_st(int k, int c) { const int kk = (k & ~0xC) | ((k & 4) << 1) | ((k & 8) >> 1); return ((kk >> 3) * 4 + (c >> 5)) * 512 + ((kk & 7) * 32 + (c & 31)) * 2; }
; __device__ __forceinline__ int v_rd_base(int lane) { return ((lane & 3) << 3) | (((lane >> 2) & 3) << 6) | (((lane >> 4) & 1) << 5) | (((lane >> 5) & 1) << 8); }
; template <int OFF> __device__ __forceinline__ s16x4 tr_read(int vb) {
;   s16x4 r; asm volatile("ds_read_b64_tr_b16 %0, %1 offset:%2" : "=&v"(r) : "v"(vb), "i"(OFF) : "memory"); return r;
; }
; template <int D0> __device__ __forceinline__ void pv_one(f32x16& od, int vb, bf16x8 pa0, bf16x8 pa1, bf16x8 pa2, bf16x8 pa3) {
;   const s16x4 l0 = tr_read<v_rd_off(D0, 0, 0)>(vb), h0 = tr_read<v_rd_off(D0, 0, 1)>(vb), l1 = tr_read<v_rd_off(D0, 1, 0)>(vb), h1 = tr_read<v_rd_off(D0, 1, 1)>(vb);
;   const s16x4 l2 = tr_read<v_rd_off(D0, 2, 0)>(vb), h2 = tr_read<v_rd_off(D0, 2, 1)>(vb), l3 = tr_read<v_rd_off(D0, 3, 0)>(vb), h3 = tr_read<v_rd_off(D0, 3, 1)>(vb);
;   asm volatile("s_waitcnt lgkmcnt(0)" ::: "memory"); SBAR();
;     ...
;   od = __builtin_amdgcn_mfma_f32_32x32x16_bf16(pa0, PK(l0, h0), od, 0, 0, 0);
	v_add_u32_e32 v211, s10, v182
	ds_read_b128 v[66:69], v211 offset:49152
	ds_read_b128 v[82:85], v211 offset:50176
	ds_read_b128 v[146:149], v211 offset:51200
	ds_read_b128 v[150:153], v211 offset:52224
	v_exp_f32_e32 v155, v155
	s_waitcnt lgkmcnt(3)
	s_setprio 1
	v_mfma_f32_32x32x16_bf16 v[66:81], v[66:69], v[98:101], 0
	v_exp_f32_e32 v156, v156
	v_exp_f32_e32 v157, v157
	v_exp_f32_e32 v158, v158
	v_exp_f32_e32 v159, v159
	v_exp_f32_e32 v160, v160
	v_exp_f32_e32 v161, v161
	v_exp_f32_e32 v198, v198
	s_waitcnt lgkmcnt(2)
	v_mfma_f32_32x32x16_bf16 v[82:97], v[82:85], v[98:101], 0
	v_exp_f32_e32 v199, v199
	v_exp_f32_e32 v200, v200
	v_exp_f32_e32 v201, v201
	v_exp_f32_e32 v202, v202
	v_exp_f32_e32 v203, v203
	v_exp_f32_e32 v204, v204
	v_exp_f32_e32 v205, v205
	s_waitcnt lgkmcnt(1)
	v_mfma_f32_32x32x16_bf16 v[66:81], v[146:149], v[102:105], v[66:81]
	v_exp_f32_e32 v226, v154
	v_cvt_pk_bf16_f32 v154, v155, v156
	s_waitcnt lgkmcnt(0)
	v_mfma_f32_32x32x16_bf16 v[82:97], v[150:153], v[102:105], v[82:97]
	ds_read_b128 v[146:149], v211 offset:53248
	ds_read_b128 v[150:153], v211 offset:54272
	s_waitcnt lgkmcnt(1)
	v_mfma_f32_32x32x16_bf16 v[66:81], v[146:149], v[106:109], v[66:81]
	s_waitcnt lgkmcnt(0)
	v_mfma_f32_32x32x16_bf16 v[82:97], v[150:153], v[106:109], v[82:97]
	ds_read_b128 v[146:149], v211 offset:55296
	ds_read_b128 v[150:153], v211 offset:56320
	s_waitcnt lgkmcnt(1)
	v_mfma_f32_32x32x16_bf16 v[66:81], v[146:149], v[110:113], v[66:81]
	s_waitcnt lgkmcnt(0)
	v_mfma_f32_32x32x16_bf16 v[82:97], v[150:153], v[110:113], v[82:97]
	ds_read_b128 v[146:149], v211 offset:57344
	ds_read_b128 v[150:153], v211 offset:58368
	s_waitcnt lgkmcnt(1)
	v_mfma_f32_32x32x16_bf16 v[66:81], v[146:149], v[114:117], v[66:81]
	s_waitcnt lgkmcnt(0)
	v_mfma_f32_32x32x16_bf16 v[82:97], v[150:153], v[114:117], v[82:97]
	ds_read_b128 v[146:149], v211 offset:59392
	ds_read_b128 v[150:153], v211 offset:60416
	s_waitcnt lgkmcnt(1)
	v_mfma_f32_32x32x16_bf16 v[66:81], v[146:149], v[118:121], v[66:81]
	s_waitcnt lgkmcnt(0)
	v_mfma_f32_32x32x16_bf16 v[82:97], v[150:153], v[118:121], v[82:97]
	ds_read_b128 v[146:149], v211 offset:61440
	ds_read_b128 v[150:153], v211 offset:62464
	s_waitcnt lgkmcnt(1)
	v_mfma_f32_32x32x16_bf16 v[66:81], v[146:149], v[122:125], v[66:81]
	s_waitcnt lgkmcnt(0)
	v_mfma_f32_32x32x16_bf16 v[82:97], v[150:153], v[122:125], v[82:97]
	ds_read_b128 v[146:149], v211 offset:63488
	ds_read_b128 v[150:153], v211 offset:64512
	s_waitcnt lgkmcnt(1)
	v_mfma_f32_32x32x16_bf16 v[66:81], v[146:149], v[126:129], v[66:81]
	v_add_f32_e32 v146, v207, v206
	v_add_f32_e32 v146, v212, v146
	v_add_f32_e32 v146, v213, v146
	v_add_f32_e32 v146, v214, v146
	v_add_f32_e32 v146, v215, v146
	v_add_f32_e32 v146, v216, v146
	v_add_f32_e32 v146, v217, v146
	v_add_f32_e32 v146, v218, v146
	v_add_f32_e32 v146, v219, v146
	v_add_f32_e32 v146, v220, v146
	v_add_f32_e32 v146, v221, v146
	v_add_f32_e32 v146, v222, v146
	v_add_f32_e32 v146, v223, v146
	v_add_f32_e32 v146, v224, v146
	v_add_f32_e32 v146, v225, v146
	v_add_f32_e32 v146, v155, v146
	v_add_f32_e32 v146, v156, v146
	v_add_f32_e32 v146, v157, v146
	v_add_f32_e32 v146, v158, v146
	v_add_f32_e32 v146, v159, v146
	v_add_f32_e32 v146, v160, v146
	v_add_f32_e32 v146, v161, v146
	v_add_f32_e32 v146, v198, v146
	v_add_f32_e32 v146, v199, v146
	v_add_f32_e32 v146, v200, v146
	s_waitcnt lgkmcnt(0)
	v_mfma_f32_32x32x16_bf16 v[82:97], v[150:153], v[126:129], v[82:97]
	s_setprio 0
	v_add_f32_e32 v146, v201, v146
	v_add_f32_e32 v146, v202, v146
	v_add_f32_e32 v146, v203, v146
	v_add_f32_e32 v146, v204, v146
	v_add_f32_e32 v146, v205, v146
	v_add_f32_e32 v210, v226, v146
	v_mov_b32_e32 v211, v210
	v_cvt_pk_bf16_f32 v146, v206, v207
	v_cvt_pk_bf16_f32 v147, v212, v213
	v_cvt_pk_bf16_f32 v148, v214, v215
	v_cvt_pk_bf16_f32 v149, v216, v217
	v_cvt_pk_bf16_f32 v150, v218, v219
	v_cvt_pk_bf16_f32 v151, v220, v221
	v_cvt_pk_bf16_f32 v152, v222, v223
	v_cvt_pk_bf16_f32 v153, v224, v225
	v_cvt_pk_bf16_f32 v155, v157, v158
	v_cvt_pk_bf16_f32 v156, v159, v160
	v_cvt_pk_bf16_f32 v157, v161, v198
	v_cvt_pk_bf16_f32 v158, v199, v200
	v_cvt_pk_bf16_f32 v159, v201, v202
	v_cvt_pk_bf16_f32 v160, v203, v204
	v_cvt_pk_bf16_f32 v161, v205, v226
	v_permlane32_swap_b32_e32 v210, v211
	v_permlane32_swap_b32_e32 v146, v148
	v_permlane32_swap_b32_e32 v147, v149
	v_permlane32_swap_b32_e32 v150, v152
	v_permlane32_swap_b32_e32 v151, v153
	v_permlane32_swap_b32_e32 v154, v156
	v_permlane32_swap_b32_e32 v155, v157
	v_permlane32_swap_b32_e32 v158, v160
	v_permlane32_swap_b32_e32 v159, v161
	s_and_b64 vcc, exec, s[40:41]
	s_cbranch_vccz .Latt_nomask
	v_mov_b32_e32 v74, v246
	v_mov_b32_e32 v75, v246
	v_mov_b32_e32 v76, v246
	v_mov_b32_e32 v77, v246
	v_mov_b32_e32 v78, v246
	v_mov_b32_e32 v79, v246
	v_mov_b32_e32 v80, v246
	v_mov_b32_e32 v81, v246
	v_mov_b32_e32 v82, v246
	v_mov_b32_e32 v83, v246
	v_mov_b32_e32 v84, v246
	v_mov_b32_e32 v85, v246
	v_mov_b32_e32 v86, v246
	v_mov_b32_e32 v87, v246
	v_mov_b32_e32 v88, v246
	v_mov_b32_e32 v89, v246
	v_mov_b32_e32 v90, v246
	v_mov_b32_e32 v91, v246
	v_mov_b32_e32 v92, v246
	v_mov_b32_e32 v93, v246
	v_mov_b32_e32 v94, v246
	v_mov_b32_e32 v95, v246
	v_mov_b32_e32 v96, v246
	v_mov_b32_e32 v97, v246

; #define SBAR() __builtin_amdgcn_sched_barrier(0)
; template <int D0> __device__ __forceinline__ void pv_one(f32x16& od, int vb, bf16x8 pa0, bf16x8 pa1, bf16x8 pa2, bf16x8 pa3) {
;   const s16x4 l0 = tr_read<v_rd_off(D0, 0, 0)>(vb), h0 = tr_read<v_rd_off(D0, 0, 1)>(vb), l1 = tr_read<v_rd_off(D0, 1, 0)>(vb), h1 = tr_read<v_rd_off(D0, 1, 1)>(vb);
;   const s16x4 l2 = tr_read<v_rd_off(D0, 2, 0)>(vb), h2 = tr_read<v_rd_off(D0, 2, 1)>(vb), l3 = tr_read<v_rd_off(D0, 3, 0)>(vb), h3 = tr_read<v_rd_off(D0, 3, 1)>(vb);
;   asm volatile("s_waitcnt lgkmcnt(0)" ::: "memory"); SBAR();
;     ...
;   od = __builtin_amdgcn_mfma_f32_32x32x16_bf16(pa0, PK(l0, h0), od, 0, 0, 0);
;   od = __builtin_amdgcn_mfma_f32_32x32x16_bf16(pa1, PK(l1, h1), od, 0, 0, 0);
;   od = __builtin_amdgcn_mfma_f32_32x32x16_bf16(pa2, PK(l2, h2), od, 0, 0, 0);
;   od = __builtin_amdgcn_mfma_f32_32x32x16_bf16(pa3, PK(l3, h3), od, 0, 0, 0);
;     ...
; }
; __device__ __forceinline__ void pv_d0(f32x16* o, int vb, bf16x8 pa0, bf16x8 pa1, bf16x8 pa2, bf16x8 pa3) {
;   pv_one<0>(o[0], vb, pa0, pa1, pa2, pa3); pv_one<1>(o[1], vb, pa0, pa1, pa2, pa3); pv_one<2>(o[2], vb, pa0, pa1, pa2, pa3); pv_one<3>(o[3], vb, pa0, pa1, pa2, pa3);
; }
.LBB0_266:
	s_waitcnt lgkmcnt(6)
	s_nop 0
	s_setprio 1
	v_mfma_f32_32x32x16_bf16 v[2:17], v[146:149], v[212:215], v[2:17]
	ds_read_b64_tr_b16 v[212:213], v198 offset:0x200
	ds_read_b64_tr_b16 v[214:215], v198 offset:0xa00
	s_waitcnt lgkmcnt(6)
	v_mfma_f32_32x32x16_bf16 v[2:17], v[150:153], v[216:219], v[2:17]
	ds_read_b64_tr_b16 v[216:217], v198 offset:0x1200
	ds_read_b64_tr_b16 v[218:219], v198 offset:0x1a00
	s_waitcnt lgkmcnt(6)
	v_mfma_f32_32x32x16_bf16 v[2:17], v[154:157], v[220:223], v[2:17]
	ds_read_b64_tr_b16 v[220:221], v198 offset:0x2200
	ds_read_b64_tr_b16 v[222:223], v198 offset:0x2a00
	s_waitcnt lgkmcnt(6)
	v_mfma_f32_32x32x16_bf16 v[2:17], v[158:161], v[224:227], v[2:17]
	ds_read_b64_tr_b16 v[224:225], v198 offset:0x3200
	ds_read_b64_tr_b16 v[226:227], v198 offset:0x3a00
	s_waitcnt lgkmcnt(6)
	v_mfma_f32_32x32x16_bf16 v[50:65], v[146:149], v[212:215], v[50:65]
	ds_read_b64_tr_b16 v[212:213], v198 offset:0x400
	ds_read_b64_tr_b16 v[214:215], v198 offset:0xc00
	s_waitcnt lgkmcnt(6)
	v_mfma_f32_32x32x16_bf16 v[50:65], v[150:153], v[216:219], v[50:65]
	ds_read_b64_tr_b16 v[216:217], v198 offset:0x1400
	ds_read_b64_tr_b16 v[218:219], v198 offset:0x1c00
	s_waitcnt lgkmcnt(6)
	v_mfma_f32_32x32x16_bf16 v[50:65], v[154:157], v[220:223], v[50:65]
	ds_read_b64_tr_b16 v[220:221], v198 offset:0x2400
	ds_read_b64_tr_b16 v[222:223], v198 offset:0x2c00
	s_waitcnt lgkmcnt(6)
	v_mfma_f32_32x32x16_bf16 v[50:65], v[158:161], v[224:227], v[50:65]
	ds_read_b64_tr_b16 v[224:225], v198 offset:0x3400
	ds_read_b64_tr_b16 v[226:227], v198 offset:0x3c00
	s_waitcnt lgkmcnt(6)
	v_mfma_f32_32x32x16_bf16 v[34:49], v[146:149], v[212:215], v[34:49]
	ds_read_b64_tr_b16 v[212:213], v198 offset:0x600
	ds_read_b64_tr_b16 v[214:215], v198 offset:0xe00
	s_waitcnt lgkmcnt(6)
	v_mfma_f32_32x32x16_bf16 v[34:49], v[150:153], v[216:219], v[34:49]
	ds_read_b64_tr_b16 v[216:217], v198 offset:0x1600
	ds_read_b64_tr_b16 v[218:219], v198 offset:0x1e00
	s_waitcnt lgkmcnt(6)
	v_mfma_f32_32x32x16_bf16 v[34:49], v[154:157], v[220:223], v[34:49]
	ds_read_b64_tr_b16 v[220:221], v198 offset:0x2600
	ds_read_b64_tr_b16 v[222:223], v198 offset:0x2e00
	s_waitcnt lgkmcnt(6)
	v_mfma_f32_32x32x16_bf16 v[34:49], v[158:161], v[224:227], v[34:49]
	ds_read_b64_tr_b16 v[224:225], v198 offset:0x3600
	ds_read_b64_tr_b16 v[226:227], v198 offset:0x3e00
	s_waitcnt lgkmcnt(6)
	v_mfma_f32_32x32x16_bf16 v[18:33], v[146:149], v[212:215], v[18:33]
	v_max_f32_e32 v230, v66, v67
	v_max3_f32 v230, v230, v68, v69
	v_max3_f32 v230, v230, v70, v71
	v_max3_f32 v230, v230, v72, v73
	v_max3_f32 v230, v230, v74, v75
	v_max3_f32 v230, v230, v76, v77
	v_max3_f32 v230, v230, v78, v79
	s_waitcnt lgkmcnt(4)
	v_mfma_f32_32x32x16_bf16 v[18:33], v[150:153], v[216:219], v[18:33]
	v_max3_f32 v230, v230, v80, v81
	v_max3_f32 v230, v230, v82, v83
	v_max3_f32 v230, v230, v84, v85
	v_max3_f32 v230, v230, v86, v87
	v_max3_f32 v230, v230, v88, v89
	v_max3_f32 v230, v230, v90, v91
	v_max3_f32 v230, v230, v92, v93
	v_max3_f32 v230, v230, v94, v95
	s_waitcnt lgkmcnt(2)
	v_mfma_f32_32x32x16_bf16 v[18:33], v[154:157], v[220:223], v[18:33]
	v_max3_f32 v230, v230, v96, v97
	v_mov_b32_e32 v231, v230
	s_nop 1
	v_permlane32_swap_b32_e32 v230, v231
	v_max_f32_e32 v230, v230, v231
	v_sub_f32_e32 v231, v230, v209
	v_cmp_ge_f32_e32 vcc, s25, v231
	v_max_f32_e32 v231, v209, v230
	s_waitcnt lgkmcnt(0)
	v_mfma_f32_32x32x16_bf16 v[18:33], v[158:161], v[224:227], v[18:33]
	s_setprio 0
	v_sub_f32_e32 v230, v209, v231
	v_mul_f32_e32 v230, 0x3e0293ee, v230
	s_cmp_eq_u64 vcc, exec
	v_exp_f32_e32 v230, v230
	s_cselect_b64 s[40:41], -1, 0
	s_add_i32 s0, s8, 0
	v_cndmask_b32_e64 v230, v230, 1.0, s[40:41]
	v_cmp_gt_f32_e32 vcc, 1.0, v230
	s_cbranch_vccz .LBB0_270
	s_and_saveexec_b64 s[0:1], s[38:39]
	ds_write_b32 v190, v230 offset:128
	s_or_b64 exec, exec, s[0:1]
	s_waitcnt lgkmcnt(0)
	v_add_u32_e32 v236, v173, v181
	ds_read_b128 v[232:235], v236 offset:224
	ds_read_b128 v[130:133], v236 offset:192
	ds_read_b128 v[134:137], v236 offset:160
	ds_read_b128 v[138:141], v236 offset:128
	s_waitcnt lgkmcnt(3)
	v_pk_mul_f32 v[14:15], v[14:15], v[232:233]
	s_waitcnt lgkmcnt(2)
	v_pk_mul_f32 v[10:11], v[10:11], v[130:131]
	s_waitcnt lgkmcnt(1)
	v_pk_mul_f32 v[6:7], v[6:7], v[134:135]
	v_pk_mul_f32 v[16:17], v[16:17], v[234:235]
	v_pk_mul_f32 v[12:13], v[12:13], v[132:133]
	v_pk_mul_f32 v[8:9], v[8:9], v[136:137]
	s_waitcnt lgkmcnt(0)
	v_pk_mul_f32 v[4:5], v[4:5], v[140:141]
	v_pk_mul_f32 v[2:3], v[2:3], v[138:139]
	v_pk_mul_f32 v[62:63], v[62:63], v[232:233]
	v_pk_mul_f32 v[58:59], v[58:59], v[130:131]
	v_pk_mul_f32 v[54:55], v[54:55], v[134:135]
	v_pk_mul_f32 v[64:65], v[64:65], v[234:235]
	v_pk_mul_f32 v[60:61], v[60:61], v[132:133]
	v_pk_mul_f32 v[56:57], v[56:57], v[136:137]
	v_pk_mul_f32 v[52:53], v[52:53], v[140:141]
	v_pk_mul_f32 v[50:51], v[50:51], v[138:139]
	v_pk_mul_f32 v[46:47], v[46:47], v[232:233]
	v_pk_mul_f32 v[42:43], v[42:43], v[130:131]
	v_pk_mul_f32 v[38:39], v[38:39], v[134:135]
	v_pk_mul_f32 v[48:49], v[48:49], v[234:235]
	v_pk_mul_f32 v[44:45], v[44:45], v[132:133]
	v_pk_mul_f32 v[40:41], v[40:41], v[136:137]
	v_pk_mul_f32 v[36:37], v[36:37], v[140:141]
	v_pk_mul_f32 v[34:35], v[34:35], v[138:139]
	v_pk_mul_f32 v[30:31], v[30:31], v[232:233]
	v_pk_mul_f32 v[26:27], v[26:27], v[130:131]
	v_pk_mul_f32 v[22:23], v[22:23], v[134:135]
	v_pk_mul_f32 v[32:33], v[32:33], v[234:235]
	v_pk_mul_f32 v[28:29], v[28:29], v[132:133]
	v_pk_mul_f32 v[24:25], v[24:25], v[136:137]
	v_pk_mul_f32 v[20:21], v[20:21], v[140:141]
	v_pk_mul_f32 v[18:19], v[18:19], v[138:139]
